# stick-breaking loop keeps log-probabilities in base 2 (scores scaled by 0.125*log2e), dropping 32 multiplies per tile
# baseline (speedup 1.0000x reference)
; __device__ __forceinline__ int crow(int r, int hi) { return (r & 3) + 8 * (r >> 2) + 4 * hi; }
; template <bool DRY> __device__ __forceinline__ void sb_unit(int b, int h, int qi, bf16_t* Pm, const bf16_t* VT) {
;     ...
;         sb_load(nxt, Pm, VT, tok0, (kt > 0 ? kt - 1 : 0) * 32, h, r32, hi);
;         f32x16 p = {};
; #pragma unroll
;         for (int s = 0; s < 4; ++s) p = __builtin_amdgcn_mfma_f32_32x32x16_bf16(cur.kf[s], qf[s], p, 0, 0, 0);
;         const bool diag = (kt == qi);
;         float lk[16], inner[16], Tg[4], TP[4], pre[4];
; #pragma unroll
;         for (int r = 0; r < 16; ++r) {
;             const float z = p[r] * 0.125f; p[r] = z;
;             const float e = __expf(-fabsf(z)); const float sp = fmaxf(z, 0.f) + __logf(1.f + e);
;             const bool valid = !diag || (crow(r, hi) < r32);
;             lk[r] = valid ? -sp : 0.f;
.LBB0_742:
	v_med3_i32 v36, v100, 0, 1
	v_lshlrev_b32_e32 v36, 5, v36
	s_mov_b32 s4, 0x208000
	v_sub_u32_e32 v40, v99, v36
	v_add_co_u32_e32 v36, vcc, s4, v94
	v_mov_b32_e32 v41, v2
	s_nop 0
	v_addc_co_u32_e32 v37, vcc, 0, v95, vcc
	global_load_dwordx4 v[156:159], v[36:37], off offset:32
	global_load_dwordx4 v[160:163], v[94:95], off offset:32
	global_load_dwordx4 v[164:167], v[36:37], off
	global_load_dwordx4 v[168:171], v[94:95], off
	v_mad_u64_u32 v[36:37], s[4:5], v90, s24, v[92:93]
	v_mov_b32_e32 v38, v37
	v_mad_u64_u32 v[38:39], s[4:5], v91, s24, v[38:39]
	v_mov_b32_e32 v37, v38
	global_load_dwordx4 v[152:155], v[36:37], off offset:2400
	global_load_dwordx4 v[148:151], v[36:37], off offset:2368
	global_load_dwordx4 v[144:147], v[36:37], off offset:2336
	s_nop 0
	global_load_dwordx4 v[140:143], v[36:37], off offset:2304
	v_lshl_add_u64 v[90:91], v[0:1], 0, v[40:41]
	v_lshl_add_u64 v[94:95], v[40:41], 1, v[88:89]
	s_cmp_lg_u32 s28, 0
	s_cselect_b64 s[22:23], -1, 0
	s_or_b64 s[76:77], s[44:45], s[22:23]
	s_or_b64 s[78:79], s[46:47], s[22:23]
	s_or_b64 s[80:81], s[48:49], s[22:23]
	s_or_b64 s[88:89], s[56:57], s[22:23]
	s_or_b64 s[94:95], s[62:63], s[22:23]
	s_or_b64 s[96:97], s[64:65], s[22:23]
	s_or_b64 s[84:85], s[52:53], s[22:23]
	s_or_b64 s[86:87], s[54:55], s[22:23]
	s_or_b64 s[92:93], s[60:61], s[22:23]
	s_or_b64 s[90:91], s[58:59], s[22:23]
	s_or_b64 s[82:83], s[50:51], s[22:23]
	v_add_u32_e32 v100, -1, v100
	v_subrev_u32_e32 v99, 32, v99
	s_waitcnt vmcnt(8)
	v_mfma_f32_32x32x16_bf16 v[36:51], v[172:175], v[52:55], 0
	v_mfma_f32_32x32x16_bf16 v[36:51], v[176:179], v[56:59], v[36:51]
	v_mfma_f32_32x32x16_bf16 v[36:51], v[180:183], v[60:63], v[36:51]
	v_mfma_f32_32x32x16_bf16 v[36:51], v[184:187], v[64:67], v[36:51]
	v_permlane32_swap_b32_e32 v80, v82
	v_permlane32_swap_b32_e32 v81, v83
	v_permlane32_swap_b32_e32 v72, v74
	v_permlane32_swap_b32_e32 v73, v75
	v_permlane32_swap_b32_e32 v76, v78
	v_permlane32_swap_b32_e32 v77, v79
	v_permlane32_swap_b32_e32 v68, v70
	v_permlane32_swap_b32_e32 v69, v71
	s_nop 3
	v_mul_f32_e32 v96, 0x3e38aa3b, v36
	v_exp_f32_e64 v97, -|v96|
	v_max_f32_e32 v96, 0, v96
	v_add_f32_e32 v97, 1.0, v97
	v_log_f32_e32 v97, v97
	s_nop 0
	v_add_f32_e32 v96, v97, v96
	v_cndmask_b32_e64 v103, 0, -v96, s[76:77]
	v_mul_f32_e32 v96, 0x3e38aa3b, v37
	v_exp_f32_e64 v97, -|v96|
	v_max_f32_e32 v96, 0, v96
	v_fmamk_f32 v36, v36, 0x3e38aa3b, v103
	v_add_f32_e32 v97, 1.0, v97
	v_log_f32_e32 v97, v97
	s_nop 0
	v_add_f32_e32 v96, v97, v96
	v_cndmask_b32_e64 v108, 0, -v96, s[78:79]
	v_mul_f32_e32 v96, 0x3e38aa3b, v38
	v_exp_f32_e64 v97, -|v96|
	v_max_f32_e32 v96, 0, v96
	v_add_f32_e32 v97, 1.0, v97
	v_log_f32_e32 v97, v97
	s_nop 0
	v_add_f32_e32 v96, v97, v96
	v_cndmask_b32_e64 v109, 0, -v96, s[80:81]
	v_mul_f32_e32 v96, 0x3e38aa3b, v39
	v_exp_f32_e64 v39, -|v96|
	v_max_f32_e32 v97, 0, v96
	v_add_f32_e32 v39, 1.0, v39
	v_log_f32_e32 v39, v39
	s_nop 0
	v_add_f32_e32 v110, v39, v97
	v_mul_f32_e32 v39, 0x3e38aa3b, v40
	v_exp_f32_e64 v97, -|v39|
	v_max_f32_e32 v39, 0, v39
	v_add_f32_e32 v97, 1.0, v97
	v_log_f32_e32 v97, v97
	s_nop 0
	v_add_f32_e32 v39, v97, v39
	v_mul_f32_e32 v97, 0x3e38aa3b, v41
	v_exp_f32_e64 v104, -|v97|
	v_max_f32_e32 v97, 0, v97
	v_cndmask_b32_e64 v39, 0, -v39, s[84:85]
	v_add_f32_e32 v104, 1.0, v104
	v_log_f32_e32 v104, v104
	s_nop 0
	v_add_f32_e32 v97, v104, v97
	v_mul_f32_e32 v104, 0x3e38aa3b, v42
	v_exp_f32_e64 v105, -|v104|
	v_max_f32_e32 v104, 0, v104
	v_cndmask_b32_e64 v97, 0, -v97, s[86:87]
	v_add_f32_e32 v105, 1.0, v105
	v_log_f32_e32 v105, v105
	s_nop 0
	v_add_f32_e32 v104, v105, v104
	v_cndmask_b32_e64 v111, 0, -v104, s[88:89]
	v_mul_f32_e32 v104, 0x3e38aa3b, v43
	v_exp_f32_e64 v43, -|v104|
	v_max_f32_e32 v105, 0, v104
	v_add_f32_e32 v43, 1.0, v43
	v_log_f32_e32 v43, v43
	s_nop 0
	v_add_f32_e32 v43, v43, v105
	v_mul_f32_e32 v105, 0x3e38aa3b, v44
	v_exp_f32_e64 v106, -|v105|
	v_max_f32_e32 v105, 0, v105
	v_add_f32_e32 v106, 1.0, v106
	v_log_f32_e32 v106, v106
	s_nop 0
	v_add_f32_e32 v105, v106, v105
	v_mul_f32_e32 v106, 0x3e38aa3b, v45
	v_exp_f32_e64 v107, -|v106|
	v_max_f32_e32 v106, 0, v106
	v_cndmask_b32_e64 v105, 0, -v105, s[92:93]
	v_add_f32_e32 v107, 1.0, v107
	v_log_f32_e32 v107, v107
	s_nop 0
	v_add_f32_e32 v106, v107, v106
	v_cndmask_b32_e64 v112, 0, -v106, s[94:95]
	v_mul_f32_e32 v106, 0x3e38aa3b, v46
	v_exp_f32_e64 v107, -|v106|
	v_max_f32_e32 v106, 0, v106
	v_add_f32_e32 v107, 1.0, v107
	v_log_f32_e32 v107, v107
	s_nop 0
	v_add_f32_e32 v106, v107, v106
	v_cndmask_b32_e64 v113, 0, -v106, s[96:97]
	v_mul_f32_e32 v106, 0x3e38aa3b, v47
	v_exp_f32_e64 v47, -|v106|
	v_max_f32_e32 v107, 0, v106
	v_add_f32_e32 v47, 1.0, v47
	v_log_f32_e32 v47, v47
	s_nop 0
	v_add_f32_e32 v47, v47, v107
	v_mul_f32_e32 v107, 0x3e38aa3b, v48
	v_exp_f32_e64 v114, -|v107|
	v_max_f32_e32 v107, 0, v107
	s_or_b64 s[4:5], s[66:67], s[22:23]
	v_add_f32_e32 v114, 1.0, v114
	v_log_f32_e32 v114, v114
	s_nop 0
	v_add_f32_e32 v107, v114, v107
	s_or_b64 s[6:7], s[68:69], s[22:23]
	v_cndmask_b32_e64 v114, 0, -v107, s[6:7]
	v_mul_f32_e32 v107, 0x3e38aa3b, v49
	v_exp_f32_e64 v115, -|v107|
	v_max_f32_e32 v107, 0, v107
	v_add_f32_e32 v115, 1.0, v115
	v_log_f32_e32 v115, v115
	s_nop 0
	v_add_f32_e32 v107, v115, v107
	s_or_b64 s[8:9], s[70:71], s[22:23]
	v_cndmask_b32_e64 v115, 0, -v107, s[8:9]
	v_mul_f32_e32 v107, 0x3e38aa3b, v50
	v_exp_f32_e64 v116, -|v107|
	v_max_f32_e32 v107, 0, v107
	v_add_f32_e32 v116, 1.0, v116
	v_log_f32_e32 v116, v116
	s_nop 0
	v_add_f32_e32 v107, v116, v107
	s_or_b64 s[10:11], s[72:73], s[22:23]
	v_cndmask_b32_e64 v116, 0, -v107, s[10:11]
	v_mul_f32_e32 v107, 0x3e38aa3b, v51
	v_exp_f32_e64 v117, -|v107|
	v_max_f32_e32 v107, 0, v107
	v_add_f32_e32 v117, 1.0, v117
	v_log_f32_e32 v117, v117
	s_nop 0
	v_add_f32_e32 v107, v117, v107
	s_or_b64 vcc, s[74:75], s[22:23]
	v_cndmask_b32_e64 v117, 0, -v107, vcc
	v_add_f32_e32 v118, v117, v116
	v_add_f32_e32 v119, v115, v118
	v_add_f32_e32 v107, v114, v119
	ds_bpermute_b32 v120, v101, v107
	v_fmac_f32_e32 v114, 0x3e38aa3b, v48
	v_fmac_f32_e32 v115, 0x3e38aa3b, v49
	v_fmac_f32_e32 v116, 0x3e38aa3b, v50
	s_waitcnt lgkmcnt(0)
; __device__ __forceinline__ unsigned cvtpk(float lo, float hi) { f32x2_t v = {lo, hi}; bf16x2_t b = __builtin_convertvector(v, bf16x2_t); return __builtin_bit_cast(unsigned, b); }
; __device__ __forceinline__ int crow(int r, int hi) { return (r & 3) + 8 * (r >> 2) + 4 * hi; }
; template <bool DRY> __device__ __forceinline__ void sb_unit(int b, int h, int qi, bf16_t* Pm, const bf16_t* VT) {
;     ...
;         }
; #pragma unroll
;         for (int g = 0; g < 4; ++g) {
;             const float s3 = lk[4 * g + 3], s2 = s3 + lk[4 * g + 2], s1 = s2 + lk[4 * g + 1];
;             inner[4 * g + 3] = 0.f; inner[4 * g + 2] = s3; inner[4 * g + 1] = s2; inner[4 * g] = s1; Tg[g] = s1 + lk[4 * g];
;             TP[g] = __shfl_xor(Tg[g], 32);
;         }
;         float run = 0.f;
; #pragma unroll
;         for (int g = 3; g >= 0; --g) { pre[g] = run + (hi == 0 ? TP[g] : 0.f); run += Tg[g] + TP[g]; }
; #pragma unroll
;         for (int r = 0; r < 16; ++r) {
;             const bool valid = !diag || (crow(r, hi) < r32);
;             const float ex = fminf(p[r] + lk[r] + R + pre[r >> 2] + inner[r], 0.f);
;             p[r] = valid ? __expf(ex) : 0.f;
;         }
;         R += run;
; #pragma unroll
;         for (int s = 0; s < 2; ++s) {
;             const u32x4 pw = (u32x4){cvtpk(p[8 * s + 0], p[8 * s + 1]), cvtpk(p[8 * s + 2], p[8 * s + 3]), cvtpk(p[8 * s + 4], p[8 * s + 5]), cvtpk(p[8 * s + 6], p[8 * s + 7])};
;             const bf16x8 pf = __builtin_bit_cast(bf16x8, pw);
;             const s16x4 l0 = cur.v[4 * s], h0 = cur.v[4 * s + 1], l1 = cur.v[4 * s + 2], h1 = cur.v[4 * s + 3];
;             const bf16x8 v0 = (bf16x8){l0[0], l0[1], l0[2], l0[3], h0[0], h0[1], h0[2], h0[3]};
;             const bf16x8 v1 = (bf16x8){l1[0], l1[1], l1[2], l1[3], h1[0], h1[1], h1[2], h1[3]};
;             o0 = __builtin_amdgcn_mfma_f32_32x32x16_bf16(v0, pf, o0, 0, 0, 0);
;             o1 = __builtin_amdgcn_mfma_f32_32x32x16_bf16(v1, pf, o1, 0, 0, 0);
;         }
;         if (__all(R < -104.f)) break;
	v_add_f32_e32 v121, 0, v120
	v_add_f32_e32 v107, v107, v120
	v_add_f32_e32 v120, v102, v36
	v_fmamk_f32 v36, v37, 0x3e38aa3b, v108
	v_add_f32_e32 v122, v102, v36
	v_fmamk_f32 v36, v38, 0x3e38aa3b, v109
	v_add_f32_e32 v123, v102, v36
	v_fmamk_f32 v36, v40, 0x3e38aa3b, v39
	v_add_f32_e32 v124, v102, v36
	v_fmamk_f32 v36, v41, 0x3e38aa3b, v97
	v_add_f32_e32 v125, v102, v36
	v_fmamk_f32 v36, v42, 0x3e38aa3b, v111
	v_add_f32_e32 v126, v102, v36
	v_fmamk_f32 v36, v44, 0x3e38aa3b, v105
	v_add_f32_e32 v127, v102, v36
	v_fmamk_f32 v36, v45, 0x3e38aa3b, v112
	v_add_f32_e32 v128, v102, v36
	v_fmamk_f32 v36, v46, 0x3e38aa3b, v113
	v_add_f32_e32 v46, v102, v36
	v_cndmask_b32_e64 v36, 0, -v47, s[4:5]
	v_add_f32_e32 v47, v36, v113
	v_add_f32_e32 v112, v112, v47
	v_add_f32_e32 v38, v105, v112
	ds_bpermute_b32 v40, v101, v38
	v_add_f32_e32 v107, 0, v107
	v_cndmask_b32_e64 v121, 0, v121, s[12:13]
	s_waitcnt lgkmcnt(0)
	v_add_f32_e32 v38, v38, v40
	v_add_f32_e32 v105, v38, v107
	v_cndmask_b32_e64 v38, 0, -v43, s[90:91]
	v_add_f32_e32 v111, v38, v111
	v_add_f32_e32 v113, v97, v111
	v_cndmask_b32_e64 v37, 0, v40, s[12:13]
	v_add_f32_e32 v40, v39, v113
	ds_bpermute_b32 v41, v101, v40
	s_waitcnt lgkmcnt(0)
	v_cndmask_b32_e64 v39, 0, v41, s[12:13]
	v_add_f32_e32 v42, v40, v41
	v_pk_add_f32 v[40:41], v[104:105], v[38:39]
	v_add_f32_e32 v97, v42, v105
	v_cndmask_b32_e64 v42, 0, -v110, s[82:83]
	v_add_f32_e32 v39, v102, v40
	v_add_f32_e32 v40, v42, v109
	v_add_f32_e32 v104, v108, v40
	v_add_f32_e32 v44, v103, v104
	ds_bpermute_b32 v45, v101, v44
	s_waitcnt lgkmcnt(0)
	v_cndmask_b32_e64 v43, 0, v45, s[12:13]
	v_add_f32_e32 v103, v44, v45
	v_pk_add_f32 v[44:45], v[96:97], v[42:43]
	v_add_f32_e32 v97, v103, v97
	v_add_f32_e32 v43, v102, v44
	v_add_f32_e32 v44, v120, v45
	v_add_f32_e32 v44, v104, v44
	v_add_f32_e32 v104, v126, v41
	v_add_f32_e32 v38, v38, v104
	v_exp_f32_e64 v38, v38 clamp
	v_add_f32_e32 v96, v122, v45
	v_add_f32_e32 v40, v40, v96
	v_add_f32_e32 v96, v123, v45
	v_cndmask_b32_e64 v104, 0, v38, s[88:89]
	v_add_f32_e32 v38, v39, v41
	v_exp_f32_e64 v38, v38 clamp
	v_add_f32_e32 v42, v42, v96
	v_add_f32_e32 v43, v43, v45
	v_add_f32_e32 v45, v124, v41
	v_add_f32_e32 v96, v125, v41
	v_cndmask_b32_e64 v41, 0, v38, s[90:91]
	v_pk_add_f32 v[38:39], v[106:107], v[36:37]
	v_add_f32_e32 v45, v113, v45
	v_add_f32_e32 v37, v127, v39
	v_add_f32_e32 v37, v112, v37
	v_exp_f32_e64 v37, v37 clamp
	v_add_f32_e32 v96, v111, v96
	v_cndmask_b32_e64 v105, 0, v37, s[92:93]
	v_add_f32_e32 v37, v128, v39
	v_add_f32_e32 v37, v47, v37
	v_exp_f32_e64 v37, v37 clamp
	s_nop 0
	v_cndmask_b32_e64 v47, 0, v37, s[94:95]
	v_add_f32_e32 v37, v46, v39
	v_add_f32_e32 v36, v36, v37
	v_exp_f32_e64 v36, v36 clamp
	s_nop 0
	v_cndmask_b32_e64 v46, 0, v36, s[96:97]
	v_add_f32_e32 v36, v102, v38
	v_add_f32_e32 v36, v36, v39
	v_exp_f32_e64 v36, v36 clamp
	s_nop 0
	v_cndmask_b32_e64 v106, 0, v36, s[4:5]
	v_add_f32_e32 v36, v102, v114
	v_add_f32_e32 v36, v121, v36
	v_add_f32_e32 v36, v119, v36
	v_exp_f32_e64 v36, v36 clamp
	v_exp_f32_e64 v44, v44 clamp
	v_exp_f32_e64 v40, v40 clamp
	v_cndmask_b32_e64 v48, 0, v36, s[6:7]
	v_add_f32_e32 v36, v102, v115
	v_add_f32_e32 v36, v121, v36
	v_add_f32_e32 v36, v118, v36
	v_exp_f32_e64 v36, v36 clamp
	v_exp_f32_e64 v42, v42 clamp
	v_exp_f32_e64 v43, v43 clamp
	v_exp_f32_e64 v45, v45 clamp
	v_cndmask_b32_e64 v49, 0, v36, s[8:9]
	v_add_f32_e32 v36, v102, v116
	v_add_f32_e32 v36, v121, v36
	v_add_f32_e32 v36, v117, v36
	v_exp_f32_e64 v36, v36 clamp
	v_fmac_f32_e32 v117, 0x3e38aa3b, v51
	v_exp_f32_e64 v96, v96 clamp
	v_cndmask_b32_e64 v44, 0, v44, s[76:77]
	v_cndmask_b32_e64 v50, 0, v36, s[10:11]
	v_add_f32_e32 v36, v102, v117
	v_add_f32_e32 v36, v121, v36
	v_exp_f32_e64 v36, v36 clamp
	v_cndmask_b32_e64 v40, 0, v40, s[78:79]
	v_cndmask_b32_e64 v42, 0, v42, s[80:81]
	v_cndmask_b32_e64 v43, 0, v43, s[82:83]
	v_cndmask_b32_e64 v45, 0, v45, s[84:85]
	v_cndmask_b32_e64 v96, 0, v96, s[86:87]
	v_cndmask_b32_e32 v51, 0, v36, vcc
	v_cvt_pk_bf16_f32 v36, v44, v40
	v_cvt_pk_bf16_f32 v37, v42, v43
	v_cvt_pk_bf16_f32 v38, v45, v96
	v_cvt_pk_bf16_f32 v39, v104, v41
	v_add_f32_e32 v102, v102, v97
	s_mov_b32 s4, 0xc3160a50
	v_mfma_f32_32x32x16_bf16 v[4:19], v[80:83], v[36:39], v[4:19]
	v_cmp_gt_f32_e32 vcc, s4, v102
	s_cmp_eq_u64 vcc, exec
	s_cselect_b64 s[4:5], -1, 0
	v_cmp_eq_u32_e32 vcc, s28, v98
	s_or_b64 s[4:5], s[4:5], vcc
	s_add_i32 s28, s28, 1
	s_and_b64 s[4:5], exec, s[4:5]
	v_mfma_f32_32x32x16_bf16 v[20:35], v[76:79], v[36:39], v[20:35]
	v_cvt_pk_bf16_f32 v36, v105, v47
	v_cvt_pk_bf16_f32 v37, v46, v106
	v_cvt_pk_bf16_f32 v38, v48, v49
	v_cvt_pk_bf16_f32 v39, v50, v51
	s_or_b64 s[34:35], s[4:5], s[34:35]
	s_nop 0
	v_mfma_f32_32x32x16_bf16 v[4:19], v[72:75], v[36:39], v[4:19]
	v_mfma_f32_32x32x16_bf16 v[20:35], v[68:71], v[36:39], v[20:35]
	s_andn2_b64 exec, exec, s[34:35]
	s_cbranch_execz .Lsbu_exit
; __device__ __forceinline__ int crow(int r, int hi) { return (r & 3) + 8 * (r >> 2) + 4 * hi; }
; template <bool DRY> __device__ __forceinline__ void sb_unit(int b, int h, int qi, bf16_t* Pm, const bf16_t* VT) {
;     ...
;         sb_load(nxt, Pm, VT, tok0, (kt > 0 ? kt - 1 : 0) * 32, h, r32, hi);
;         f32x16 p = {};
; #pragma unroll
;         for (int s = 0; s < 4; ++s) p = __builtin_amdgcn_mfma_f32_32x32x16_bf16(cur.kf[s], qf[s], p, 0, 0, 0);
;         const bool diag = (kt == qi);
;         float lk[16], inner[16], Tg[4], TP[4], pre[4];
; #pragma unroll
;         for (int r = 0; r < 16; ++r) {
;             const float z = p[r] * 0.125f; p[r] = z;
;             const float e = __expf(-fabsf(z)); const float sp = fmaxf(z, 0.f) + __logf(1.f + e);
;             const bool valid = !diag || (crow(r, hi) < r32);
;             lk[r] = valid ? -sp : 0.f;
	v_med3_i32 v36, v100, 0, 1
	v_lshlrev_b32_e32 v36, 5, v36
	s_mov_b32 s4, 0x208000
	v_sub_u32_e32 v40, v99, v36
	v_add_co_u32_e32 v36, vcc, s4, v94
	v_mov_b32_e32 v41, v2
	s_nop 0
	v_addc_co_u32_e32 v37, vcc, 0, v95, vcc
	global_load_dwordx4 v[68:71], v[36:37], off offset:32
	global_load_dwordx4 v[72:75], v[94:95], off offset:32
	global_load_dwordx4 v[76:79], v[36:37], off
	global_load_dwordx4 v[80:83], v[94:95], off
	v_mad_u64_u32 v[36:37], s[4:5], v90, s24, v[92:93]
	v_mov_b32_e32 v38, v37
	v_mad_u64_u32 v[38:39], s[4:5], v91, s24, v[38:39]
	v_mov_b32_e32 v37, v38
	global_load_dwordx4 v[184:187], v[36:37], off offset:2400
	global_load_dwordx4 v[180:183], v[36:37], off offset:2368
	global_load_dwordx4 v[176:179], v[36:37], off offset:2336
	s_nop 0
	global_load_dwordx4 v[172:175], v[36:37], off offset:2304
	v_lshl_add_u64 v[90:91], v[0:1], 0, v[40:41]
	v_lshl_add_u64 v[94:95], v[40:41], 1, v[88:89]
	s_cmp_lg_u32 s28, 0
	s_cselect_b64 s[22:23], -1, 0
	s_or_b64 s[76:77], s[44:45], s[22:23]
	s_or_b64 s[78:79], s[46:47], s[22:23]
	s_or_b64 s[80:81], s[48:49], s[22:23]
	s_or_b64 s[88:89], s[56:57], s[22:23]
	s_or_b64 s[94:95], s[62:63], s[22:23]
	s_or_b64 s[96:97], s[64:65], s[22:23]
	s_or_b64 s[84:85], s[52:53], s[22:23]
	s_or_b64 s[86:87], s[54:55], s[22:23]
	s_or_b64 s[92:93], s[60:61], s[22:23]
	s_or_b64 s[90:91], s[58:59], s[22:23]
	s_or_b64 s[82:83], s[50:51], s[22:23]
	v_add_u32_e32 v100, -1, v100
	v_subrev_u32_e32 v99, 32, v99
	s_waitcnt vmcnt(8)
	v_mfma_f32_32x32x16_bf16 v[36:51], v[140:143], v[52:55], 0
	v_mfma_f32_32x32x16_bf16 v[36:51], v[144:147], v[56:59], v[36:51]
	v_mfma_f32_32x32x16_bf16 v[36:51], v[148:151], v[60:63], v[36:51]
	v_mfma_f32_32x32x16_bf16 v[36:51], v[152:155], v[64:67], v[36:51]
	v_permlane32_swap_b32_e32 v168, v170
	v_permlane32_swap_b32_e32 v169, v171
	v_permlane32_swap_b32_e32 v160, v162
	v_permlane32_swap_b32_e32 v161, v163
	v_permlane32_swap_b32_e32 v164, v166
	v_permlane32_swap_b32_e32 v165, v167
	v_permlane32_swap_b32_e32 v156, v158
	v_permlane32_swap_b32_e32 v157, v159
	s_nop 3
	v_mul_f32_e32 v96, 0x3e38aa3b, v36
	v_exp_f32_e64 v97, -|v96|
	v_max_f32_e32 v96, 0, v96
	v_add_f32_e32 v97, 1.0, v97
	v_log_f32_e32 v97, v97
	s_nop 0
	v_add_f32_e32 v96, v97, v96
	v_cndmask_b32_e64 v103, 0, -v96, s[76:77]
	v_mul_f32_e32 v96, 0x3e38aa3b, v37
	v_exp_f32_e64 v97, -|v96|
	v_max_f32_e32 v96, 0, v96
	v_fmamk_f32 v36, v36, 0x3e38aa3b, v103
	v_add_f32_e32 v97, 1.0, v97
	v_log_f32_e32 v97, v97
	s_nop 0
	v_add_f32_e32 v96, v97, v96
	v_cndmask_b32_e64 v108, 0, -v96, s[78:79]
	v_mul_f32_e32 v96, 0x3e38aa3b, v38
	v_exp_f32_e64 v97, -|v96|
	v_max_f32_e32 v96, 0, v96
	v_add_f32_e32 v97, 1.0, v97
	v_log_f32_e32 v97, v97
	s_nop 0
	v_add_f32_e32 v96, v97, v96
	v_cndmask_b32_e64 v109, 0, -v96, s[80:81]
	v_mul_f32_e32 v96, 0x3e38aa3b, v39
	v_exp_f32_e64 v39, -|v96|
	v_max_f32_e32 v97, 0, v96
	v_add_f32_e32 v39, 1.0, v39
	v_log_f32_e32 v39, v39
	s_nop 0
	v_add_f32_e32 v110, v39, v97
	v_mul_f32_e32 v39, 0x3e38aa3b, v40
	v_exp_f32_e64 v97, -|v39|
	v_max_f32_e32 v39, 0, v39
	v_add_f32_e32 v97, 1.0, v97
	v_log_f32_e32 v97, v97
	s_nop 0
	v_add_f32_e32 v39, v97, v39
	v_mul_f32_e32 v97, 0x3e38aa3b, v41
	v_exp_f32_e64 v104, -|v97|
	v_max_f32_e32 v97, 0, v97
	v_cndmask_b32_e64 v39, 0, -v39, s[84:85]
	v_add_f32_e32 v104, 1.0, v104
	v_log_f32_e32 v104, v104
	s_nop 0
	v_add_f32_e32 v97, v104, v97
	v_mul_f32_e32 v104, 0x3e38aa3b, v42
	v_exp_f32_e64 v105, -|v104|
	v_max_f32_e32 v104, 0, v104
	v_cndmask_b32_e64 v97, 0, -v97, s[86:87]
	v_add_f32_e32 v105, 1.0, v105
	v_log_f32_e32 v105, v105
	s_nop 0
	v_add_f32_e32 v104, v105, v104
	v_cndmask_b32_e64 v111, 0, -v104, s[88:89]
	v_mul_f32_e32 v104, 0x3e38aa3b, v43
	v_exp_f32_e64 v43, -|v104|
	v_max_f32_e32 v105, 0, v104
	v_add_f32_e32 v43, 1.0, v43
	v_log_f32_e32 v43, v43
	s_nop 0
	v_add_f32_e32 v43, v43, v105
	v_mul_f32_e32 v105, 0x3e38aa3b, v44
	v_exp_f32_e64 v106, -|v105|
	v_max_f32_e32 v105, 0, v105
	v_add_f32_e32 v106, 1.0, v106
	v_log_f32_e32 v106, v106
	s_nop 0
	v_add_f32_e32 v105, v106, v105
	v_mul_f32_e32 v106, 0x3e38aa3b, v45
	v_exp_f32_e64 v107, -|v106|
	v_max_f32_e32 v106, 0, v106
	v_cndmask_b32_e64 v105, 0, -v105, s[92:93]
	v_add_f32_e32 v107, 1.0, v107
	v_log_f32_e32 v107, v107
	s_nop 0
	v_add_f32_e32 v106, v107, v106
	v_cndmask_b32_e64 v112, 0, -v106, s[94:95]
	v_mul_f32_e32 v106, 0x3e38aa3b, v46
	v_exp_f32_e64 v107, -|v106|
	v_max_f32_e32 v106, 0, v106
	v_add_f32_e32 v107, 1.0, v107
	v_log_f32_e32 v107, v107
	s_nop 0
	v_add_f32_e32 v106, v107, v106
	v_cndmask_b32_e64 v113, 0, -v106, s[96:97]
	v_mul_f32_e32 v106, 0x3e38aa3b, v47
	v_exp_f32_e64 v47, -|v106|
	v_max_f32_e32 v107, 0, v106
	v_add_f32_e32 v47, 1.0, v47
	v_log_f32_e32 v47, v47
	s_nop 0
	v_add_f32_e32 v47, v47, v107
	v_mul_f32_e32 v107, 0x3e38aa3b, v48
	v_exp_f32_e64 v114, -|v107|
	v_max_f32_e32 v107, 0, v107
	s_or_b64 s[4:5], s[66:67], s[22:23]
	v_add_f32_e32 v114, 1.0, v114
	v_log_f32_e32 v114, v114
	s_nop 0
	v_add_f32_e32 v107, v114, v107
	s_or_b64 s[6:7], s[68:69], s[22:23]
	v_cndmask_b32_e64 v114, 0, -v107, s[6:7]
	v_mul_f32_e32 v107, 0x3e38aa3b, v49
	v_exp_f32_e64 v115, -|v107|
	v_max_f32_e32 v107, 0, v107
	v_add_f32_e32 v115, 1.0, v115
	v_log_f32_e32 v115, v115
	s_nop 0
	v_add_f32_e32 v107, v115, v107
	s_or_b64 s[8:9], s[70:71], s[22:23]
	v_cndmask_b32_e64 v115, 0, -v107, s[8:9]
	v_mul_f32_e32 v107, 0x3e38aa3b, v50
	v_exp_f32_e64 v116, -|v107|
	v_max_f32_e32 v107, 0, v107
	v_add_f32_e32 v116, 1.0, v116
	v_log_f32_e32 v116, v116
	s_nop 0
	v_add_f32_e32 v107, v116, v107
	s_or_b64 s[10:11], s[72:73], s[22:23]
	v_cndmask_b32_e64 v116, 0, -v107, s[10:11]
	v_mul_f32_e32 v107, 0x3e38aa3b, v51
	v_exp_f32_e64 v117, -|v107|
	v_max_f32_e32 v107, 0, v107
	v_add_f32_e32 v117, 1.0, v117
	v_log_f32_e32 v117, v117
	s_nop 0
	v_add_f32_e32 v107, v117, v107
	s_or_b64 vcc, s[74:75], s[22:23]
	v_cndmask_b32_e64 v117, 0, -v107, vcc
	v_add_f32_e32 v118, v117, v116
	v_add_f32_e32 v119, v115, v118
	v_add_f32_e32 v107, v114, v119
	ds_bpermute_b32 v120, v101, v107
	v_fmac_f32_e32 v114, 0x3e38aa3b, v48
	v_fmac_f32_e32 v115, 0x3e38aa3b, v49
	v_fmac_f32_e32 v116, 0x3e38aa3b, v50
	s_waitcnt lgkmcnt(0)
; __device__ __forceinline__ unsigned cvtpk(float lo, float hi) { f32x2_t v = {lo, hi}; bf16x2_t b = __builtin_convertvector(v, bf16x2_t); return __builtin_bit_cast(unsigned, b); }
; __device__ __forceinline__ int crow(int r, int hi) { return (r & 3) + 8 * (r >> 2) + 4 * hi; }
; template <bool DRY> __device__ __forceinline__ void sb_unit(int b, int h, int qi, bf16_t* Pm, const bf16_t* VT) {
;     ...
;         }
; #pragma unroll
;         for (int g = 0; g < 4; ++g) {
;             const float s3 = lk[4 * g + 3], s2 = s3 + lk[4 * g + 2], s1 = s2 + lk[4 * g + 1];
;             inner[4 * g + 3] = 0.f; inner[4 * g + 2] = s3; inner[4 * g + 1] = s2; inner[4 * g] = s1; Tg[g] = s1 + lk[4 * g];
;             TP[g] = __shfl_xor(Tg[g], 32);
;         }
;         float run = 0.f;
; #pragma unroll
;         for (int g = 3; g >= 0; --g) { pre[g] = run + (hi == 0 ? TP[g] : 0.f); run += Tg[g] + TP[g]; }
; #pragma unroll
;         for (int r = 0; r < 16; ++r) {
;             const bool valid = !diag || (crow(r, hi) < r32);
;             const float ex = fminf(p[r] + lk[r] + R + pre[r >> 2] + inner[r], 0.f);
;             p[r] = valid ? __expf(ex) : 0.f;
;         }
;         R += run;
; #pragma unroll
;         for (int s = 0; s < 2; ++s) {
;             const u32x4 pw = (u32x4){cvtpk(p[8 * s + 0], p[8 * s + 1]), cvtpk(p[8 * s + 2], p[8 * s + 3]), cvtpk(p[8 * s + 4], p[8 * s + 5]), cvtpk(p[8 * s + 6], p[8 * s + 7])};
;             const bf16x8 pf = __builtin_bit_cast(bf16x8, pw);
;             const s16x4 l0 = cur.v[4 * s], h0 = cur.v[4 * s + 1], l1 = cur.v[4 * s + 2], h1 = cur.v[4 * s + 3];
;             const bf16x8 v0 = (bf16x8){l0[0], l0[1], l0[2], l0[3], h0[0], h0[1], h0[2], h0[3]};
;             const bf16x8 v1 = (bf16x8){l1[0], l1[1], l1[2], l1[3], h1[0], h1[1], h1[2], h1[3]};
;             o0 = __builtin_amdgcn_mfma_f32_32x32x16_bf16(v0, pf, o0, 0, 0, 0);
;             o1 = __builtin_amdgcn_mfma_f32_32x32x16_bf16(v1, pf, o1, 0, 0, 0);
;         }
;         if (__all(R < -104.f)) break;
	v_add_f32_e32 v121, 0, v120
	v_add_f32_e32 v107, v107, v120
	v_add_f32_e32 v120, v102, v36
	v_fmamk_f32 v36, v37, 0x3e38aa3b, v108
	v_add_f32_e32 v122, v102, v36
	v_fmamk_f32 v36, v38, 0x3e38aa3b, v109
	v_add_f32_e32 v123, v102, v36
	v_fmamk_f32 v36, v40, 0x3e38aa3b, v39
	v_add_f32_e32 v124, v102, v36
	v_fmamk_f32 v36, v41, 0x3e38aa3b, v97
	v_add_f32_e32 v125, v102, v36
	v_fmamk_f32 v36, v42, 0x3e38aa3b, v111
	v_add_f32_e32 v126, v102, v36
	v_fmamk_f32 v36, v44, 0x3e38aa3b, v105
	v_add_f32_e32 v127, v102, v36
	v_fmamk_f32 v36, v45, 0x3e38aa3b, v112
	v_add_f32_e32 v128, v102, v36
	v_fmamk_f32 v36, v46, 0x3e38aa3b, v113
	v_add_f32_e32 v46, v102, v36
	v_cndmask_b32_e64 v36, 0, -v47, s[4:5]
	v_add_f32_e32 v47, v36, v113
	v_add_f32_e32 v112, v112, v47
	v_add_f32_e32 v38, v105, v112
	ds_bpermute_b32 v40, v101, v38
	v_add_f32_e32 v107, 0, v107
	v_cndmask_b32_e64 v121, 0, v121, s[12:13]
	s_waitcnt lgkmcnt(0)
	v_add_f32_e32 v38, v38, v40
	v_add_f32_e32 v105, v38, v107
	v_cndmask_b32_e64 v38, 0, -v43, s[90:91]
	v_add_f32_e32 v111, v38, v111
	v_add_f32_e32 v113, v97, v111
	v_cndmask_b32_e64 v37, 0, v40, s[12:13]
	v_add_f32_e32 v40, v39, v113
	ds_bpermute_b32 v41, v101, v40
	s_waitcnt lgkmcnt(0)
	v_cndmask_b32_e64 v39, 0, v41, s[12:13]
	v_add_f32_e32 v42, v40, v41
	v_pk_add_f32 v[40:41], v[104:105], v[38:39]
	v_add_f32_e32 v97, v42, v105
	v_cndmask_b32_e64 v42, 0, -v110, s[82:83]
	v_add_f32_e32 v39, v102, v40
	v_add_f32_e32 v40, v42, v109
	v_add_f32_e32 v104, v108, v40
	v_add_f32_e32 v44, v103, v104
	ds_bpermute_b32 v45, v101, v44
	s_waitcnt lgkmcnt(0)
	v_cndmask_b32_e64 v43, 0, v45, s[12:13]
	v_add_f32_e32 v103, v44, v45
	v_pk_add_f32 v[44:45], v[96:97], v[42:43]
	v_add_f32_e32 v97, v103, v97
	v_add_f32_e32 v43, v102, v44
	v_add_f32_e32 v44, v120, v45
	v_add_f32_e32 v44, v104, v44
	v_add_f32_e32 v104, v126, v41
	v_add_f32_e32 v38, v38, v104
	v_exp_f32_e64 v38, v38 clamp
	v_add_f32_e32 v96, v122, v45
	v_add_f32_e32 v40, v40, v96
	v_add_f32_e32 v96, v123, v45
	v_cndmask_b32_e64 v104, 0, v38, s[88:89]
	v_add_f32_e32 v38, v39, v41
	v_exp_f32_e64 v38, v38 clamp
	v_add_f32_e32 v42, v42, v96
	v_add_f32_e32 v43, v43, v45
	v_add_f32_e32 v45, v124, v41
	v_add_f32_e32 v96, v125, v41
	v_cndmask_b32_e64 v41, 0, v38, s[90:91]
	v_pk_add_f32 v[38:39], v[106:107], v[36:37]
	v_add_f32_e32 v45, v113, v45
	v_add_f32_e32 v37, v127, v39
	v_add_f32_e32 v37, v112, v37
	v_exp_f32_e64 v37, v37 clamp
	v_add_f32_e32 v96, v111, v96
	v_cndmask_b32_e64 v105, 0, v37, s[92:93]
	v_add_f32_e32 v37, v128, v39
	v_add_f32_e32 v37, v47, v37
	v_exp_f32_e64 v37, v37 clamp
	s_nop 0
	v_cndmask_b32_e64 v47, 0, v37, s[94:95]
	v_add_f32_e32 v37, v46, v39
	v_add_f32_e32 v36, v36, v37
	v_exp_f32_e64 v36, v36 clamp
	s_nop 0
	v_cndmask_b32_e64 v46, 0, v36, s[96:97]
	v_add_f32_e32 v36, v102, v38
	v_add_f32_e32 v36, v36, v39
	v_exp_f32_e64 v36, v36 clamp
	s_nop 0
	v_cndmask_b32_e64 v106, 0, v36, s[4:5]
	v_add_f32_e32 v36, v102, v114
	v_add_f32_e32 v36, v121, v36
	v_add_f32_e32 v36, v119, v36
	v_exp_f32_e64 v36, v36 clamp
	v_exp_f32_e64 v44, v44 clamp
	v_exp_f32_e64 v40, v40 clamp
	v_cndmask_b32_e64 v48, 0, v36, s[6:7]
	v_add_f32_e32 v36, v102, v115
	v_add_f32_e32 v36, v121, v36
	v_add_f32_e32 v36, v118, v36
	v_exp_f32_e64 v36, v36 clamp
	v_exp_f32_e64 v42, v42 clamp
	v_exp_f32_e64 v43, v43 clamp
	v_exp_f32_e64 v45, v45 clamp
	v_cndmask_b32_e64 v49, 0, v36, s[8:9]
	v_add_f32_e32 v36, v102, v116
	v_add_f32_e32 v36, v121, v36
	v_add_f32_e32 v36, v117, v36
	v_exp_f32_e64 v36, v36 clamp
	v_fmac_f32_e32 v117, 0x3e38aa3b, v51
	v_exp_f32_e64 v96, v96 clamp
	v_cndmask_b32_e64 v44, 0, v44, s[76:77]
	v_cndmask_b32_e64 v50, 0, v36, s[10:11]
	v_add_f32_e32 v36, v102, v117
	v_add_f32_e32 v36, v121, v36
	v_exp_f32_e64 v36, v36 clamp
	v_cndmask_b32_e64 v40, 0, v40, s[78:79]
	v_cndmask_b32_e64 v42, 0, v42, s[80:81]
	v_cndmask_b32_e64 v43, 0, v43, s[82:83]
	v_cndmask_b32_e64 v45, 0, v45, s[84:85]
	v_cndmask_b32_e64 v96, 0, v96, s[86:87]
	v_cndmask_b32_e32 v51, 0, v36, vcc
	v_cvt_pk_bf16_f32 v36, v44, v40
	v_cvt_pk_bf16_f32 v37, v42, v43
	v_cvt_pk_bf16_f32 v38, v45, v96
	v_cvt_pk_bf16_f32 v39, v104, v41
	v_add_f32_e32 v102, v102, v97
	s_mov_b32 s4, 0xc3160a50
	v_mfma_f32_32x32x16_bf16 v[4:19], v[168:171], v[36:39], v[4:19]
	v_cmp_gt_f32_e32 vcc, s4, v102
	s_cmp_eq_u64 vcc, exec
	s_cselect_b64 s[4:5], -1, 0
	v_cmp_eq_u32_e32 vcc, s28, v98
	s_or_b64 s[4:5], s[4:5], vcc
	s_add_i32 s28, s28, 1
	s_and_b64 s[4:5], exec, s[4:5]
	v_mfma_f32_32x32x16_bf16 v[20:35], v[164:167], v[36:39], v[20:35]
	v_cvt_pk_bf16_f32 v36, v105, v47
	v_cvt_pk_bf16_f32 v37, v46, v106
	v_cvt_pk_bf16_f32 v38, v48, v49
	v_cvt_pk_bf16_f32 v39, v50, v51
	s_or_b64 s[34:35], s[4:5], s[34:35]
	s_nop 0
	v_mfma_f32_32x32x16_bf16 v[4:19], v[160:163], v[36:39], v[4:19]
	v_mfma_f32_32x32x16_bf16 v[20:35], v[156:159], v[36:39], v[20:35]
	s_andn2_b64 exec, exec, s[34:35]
	s_cbranch_execnz .LBB0_742
